# SO5b: scan side work hand-written, scalar f32 ops in skewed dependent chains, weight loads and MFMAs spread through the VALU work (on v39)
# speedup vs baseline: 1.0047x; 1.0047x over previous
.LBB0_436:
	s_waitcnt vmcnt(0)
	s_or_b64 s[10:11], s[82:83], s[56:57]
	s_and_b64 vcc, exec, s[10:11]
	s_waitcnt lgkmcnt(0)
	s_barrier
	s_cbranch_vccnz .LBB0_438
	s_lshl_b32 s15, s49, 6
	s_sub_i32 s16, s63, s73
	s_add_i32 s17, s15, s0
	s_sub_i32 s18, s71, s17
	s_add_i32 s14, s15, s60
	s_sub_i32 s31, s71, s14
	s_and_b64 s[10:11], s[8:9], exec
	s_cselect_b32 s16, s15, s16
	s_cselect_b32 s17, s17, s18
	s_cselect_b32 s14, s14, s31
	v_lshrrev_b32_e32 v136, 3, v1
	v_and_b32_e32 v137, 7, v1
	v_lshlrev_b32_e32 v143, 4, v1
	v_mov_b32_e32 v144, 0
	v_mov_b32_e32 v145, 0
	v_mov_b32_e32 v146, 0
	v_mov_b32_e32 v147, 0
	v_add_u32_e32 v143, 0x22f00, v143
	v_lshlrev_b32_e32 v138, 4, v137
	v_add_u32_e32 v139, s17, v136
	v_add_u32_e32 v140, s14, v136
	ds_write_b128 v143, v[144:147]
	v_subrev_u32_e32 v98, s16, v139
	v_subrev_u32_e32 v99, s16, v140
	v_cmp_lt_i32_e32 vcc, 0, v139
	v_mad_u32_u24 v98, v98, s58, v138
	v_mad_u32_u24 v99, v99, s58, v138
	v_mov_b32_e32 v141, 0x1a580
	v_mov_b32_e32 v142, 0x1a080
	v_cndmask_b32_e32 v100, v141, v98, vcc
	v_cmp_gt_i32_e32 vcc, s33, v139
	v_lshlrev_b32_e32 v148, 5, v137
	v_add_u32_e32 v148, 0x22000, v148
	v_cndmask_b32_e32 v101, v142, v98, vcc
	v_cmp_lt_i32_e32 vcc, 0, v140
	ds_read_b128 v[168:171], v100 offset:35200
	ds_read_b128 v[172:175], v98 offset:35840
	ds_read_b128 v[176:179], v101 offset:36480
	ds_read_b128 v[192:195], v148 offset:768
	ds_read_b128 v[196:199], v148 offset:784
	v_cndmask_b32_e32 v220, v141, v99, vcc
	v_cmp_gt_i32_e32 vcc, s33, v140
	ds_read_b128 v[200:203], v148 offset:1024
	ds_read_b128 v[204:207], v148 offset:1040
	v_sub_u32_e32 v149, 7, v136
	v_cndmask_b32_e32 v221, v142, v99, vcc
	ds_read_b128 v[180:183], v100 offset:35328
	ds_read_b128 v[184:187], v98 offset:35968
	ds_read_b128 v[188:191], v101 offset:36608
	v_cndmask_b32_e64 v149, v149, v136, s[8:9]
	v_lshl_add_u32 v149, v149, 7, v138
	v_add_u32_e32 v222, s34, v149
	v_add_u32_e32 v223, s61, v149
	v_readlane_b32 s10, v255, 25
	v_readlane_b32 s11, v255, 26
	v_lshlrev_b32_e32 v150, 7, v1
	v_lshrrev_b32_e32 v152, 1, v1
	v_and_b32_e32 v150, 0x780, v150
	v_and_b32_e32 v152, -8, v152
	v_mov_b32_e32 v151, 0
	v_lshl_add_u32 v150, v152, 1, v150
	s_mov_b32 s31, s41
	v_lshl_add_u64 v[224:225], s[10:11], 0, v[150:151]
	v_mov_b32_e32 v164, 0x4038aa3b
	v_mov_b32_e32 v165, 0x4038aa3b
	v_lshl_add_u64 v[224:225], v[224:225], 0, s[30:31]
	s_movk_i32 s10, 0x1000
	s_mov_b32 s11, 0
	v_lshl_add_u64 v[250:251], v[224:225], 0, s[10:11]
	s_mov_b32 s10, 0x40000
	v_lshl_add_u64 v[252:253], v[224:225], 0, s[10:11]
	s_mov_b32 s10, 0x41000
	s_waitcnt lgkmcnt(7)
	v_lshlrev_b32_e32 v136, 16, v168
	global_load_dwordx4 v[34:37], v[224:225], off
	v_lshlrev_b32_e32 v138, 16, v176
	v_and_b32_e32 v137, 0xffff0000, v168
	v_lshlrev_b32_e32 v140, 16, v172
	v_and_b32_e32 v139, 0xffff0000, v176
	v_lshlrev_b32_e32 v142, 16, v169
	global_load_dwordx4 v[38:41], v[224:225], off offset:64
	v_add_f32_e32 v136, v138, v136
	v_and_b32_e32 v141, 0xffff0000, v172
	v_lshlrev_b32_e32 v144, 16, v177
	v_and_b32_e32 v143, 0xffff0000, v169
	v_fma_f32 v136, v136, 0.5, -v140
	v_add_f32_e32 v137, v139, v137
	v_lshlrev_b32_e32 v146, 16, v173
	v_and_b32_e32 v145, 0xffff0000, v177
	v_lshlrev_b32_e32 v148, 16, v170
	global_load_dwordx4 v[42:45], v[224:225], off offset:2048
	s_waitcnt lgkmcnt(5)
	v_fmac_f32_e32 v140, v192, v136
	v_fma_f32 v137, v137, 0.5, -v141
	v_add_f32_e32 v142, v144, v142
	v_and_b32_e32 v147, 0xffff0000, v173
	v_lshlrev_b32_e32 v150, 16, v178
	v_and_b32_e32 v149, 0xffff0000, v170
	v_mul_f32_e32 v140, 0x4038aa3b, v140
	v_fmac_f32_e32 v141, v193, v137
	v_fma_f32 v142, v142, 0.5, -v146
	v_add_f32_e32 v143, v145, v143
	v_lshlrev_b32_e32 v152, 16, v174
	v_and_b32_e32 v151, 0xffff0000, v178
	v_lshlrev_b32_e32 v154, 16, v171
	global_load_dwordx4 v[46:49], v[224:225], off offset:2112
	v_exp_f32_e32 v140, v140
	v_mul_f32_e32 v141, 0x4038aa3b, v141
	v_fmac_f32_e32 v146, v194, v142
	v_fma_f32 v143, v143, 0.5, -v147
	v_add_f32_e32 v148, v150, v148
	v_and_b32_e32 v153, 0xffff0000, v174
	v_lshlrev_b32_e32 v156, 16, v179
	v_and_b32_e32 v155, 0xffff0000, v171
	v_lshl_add_u64 v[224:225], v[224:225], 0, s[10:11]
	v_add_f32_e32 v140, 1.0, v140
	v_exp_f32_e32 v141, v141
	v_mul_f32_e32 v146, 0x4038aa3b, v146
	v_fmac_f32_e32 v147, v195, v143
	v_fma_f32 v148, v148, 0.5, -v152
	v_add_f32_e32 v149, v151, v149
	v_lshlrev_b32_e32 v158, 16, v175
	v_and_b32_e32 v157, 0xffff0000, v179
	global_load_dwordx4 v[50:53], v[250:251], off
	v_rcp_f32_e32 v140, v140
	v_add_f32_e32 v141, 1.0, v141
	v_exp_f32_e32 v146, v146
	v_mul_f32_e32 v147, 0x4038aa3b, v147
	v_fmac_f32_e32 v152, v196, v148
	v_fma_f32 v149, v149, 0.5, -v153
	v_add_f32_e32 v154, v156, v154
	v_and_b32_e32 v159, 0xffff0000, v175
	ds_read_b128 v[168:171], v220 offset:35200
	ds_read_b128 v[172:175], v99 offset:35840
	ds_read_b128 v[176:179], v221 offset:36480
	v_fma_f32 v140, -v140, 2.0, 1.0
	v_rcp_f32_e32 v141, v141
	v_add_f32_e32 v146, 1.0, v146
	v_exp_f32_e32 v147, v147
	v_mul_f32_e32 v152, 0x4038aa3b, v152
	v_fmac_f32_e32 v153, v197, v149
	v_fma_f32 v154, v154, 0.5, -v158
	v_add_f32_e32 v155, v157, v155
	global_load_dwordx4 v[54:57], v[250:251], off offset:64
	v_fma_f32 v141, -v141, 2.0, 1.0
	v_rcp_f32_e32 v146, v146
	v_add_f32_e32 v147, 1.0, v147
	v_exp_f32_e32 v152, v152
	v_mul_f32_e32 v153, 0x4038aa3b, v153
	v_fmac_f32_e32 v158, v198, v154
	v_fma_f32 v155, v155, 0.5, -v159
	s_waitcnt lgkmcnt(3)
	v_lshlrev_b32_e32 v136, 16, v180
	v_cvt_pk_bf16_f32 v160, v140, v141
	v_fma_f32 v146, -v146, 2.0, 1.0
	v_rcp_f32_e32 v147, v147
	v_add_f32_e32 v152, 1.0, v152
	v_exp_f32_e32 v153, v153
	v_mul_f32_e32 v158, 0x4038aa3b, v158
	v_fmac_f32_e32 v159, v199, v155
	global_load_dwordx4 v[58:61], v[250:251], off offset:2048
	v_lshlrev_b32_e32 v138, 16, v188
	v_and_b32_e32 v137, 0xffff0000, v180
	v_fma_f32 v147, -v147, 2.0, 1.0
	v_rcp_f32_e32 v152, v152
	v_add_f32_e32 v153, 1.0, v153
	v_exp_f32_e32 v158, v158
	v_mul_f32_e32 v159, 0x4038aa3b, v159
	v_lshlrev_b32_e32 v140, 16, v184
	v_and_b32_e32 v139, 0xffff0000, v188
	v_lshlrev_b32_e32 v142, 16, v181
	v_cvt_pk_bf16_f32 v161, v146, v147
	v_fma_f32 v152, -v152, 2.0, 1.0
	v_rcp_f32_e32 v153, v153
	v_add_f32_e32 v158, 1.0, v158
	v_exp_f32_e32 v159, v159
	global_load_dwordx4 v[62:65], v[250:251], off offset:2112
	v_add_f32_e32 v136, v138, v136
	v_and_b32_e32 v141, 0xffff0000, v184
	v_lshlrev_b32_e32 v144, 16, v189
	v_and_b32_e32 v143, 0xffff0000, v181
	v_fma_f32 v153, -v153, 2.0, 1.0
	v_rcp_f32_e32 v158, v158
	v_add_f32_e32 v159, 1.0, v159
	v_fma_f32 v136, v136, 0.5, -v140
	v_add_f32_e32 v137, v139, v137
	v_lshlrev_b32_e32 v146, 16, v185
	v_and_b32_e32 v145, 0xffff0000, v189
	v_lshlrev_b32_e32 v148, 16, v182
	v_cvt_pk_bf16_f32 v162, v152, v153
	v_fma_f32 v158, -v158, 2.0, 1.0
	v_rcp_f32_e32 v159, v159
	global_load_dwordx4 v[66:69], v[252:253], off
	v_fmac_f32_e32 v140, v200, v136
	v_fma_f32 v137, v137, 0.5, -v141
	v_add_f32_e32 v142, v144, v142
	v_and_b32_e32 v147, 0xffff0000, v185
	v_lshlrev_b32_e32 v150, 16, v190
	v_and_b32_e32 v149, 0xffff0000, v182
	v_fma_f32 v159, -v159, 2.0, 1.0
	v_fmac_f32_e32 v141, v201, v137
	v_fma_f32 v142, v142, 0.5, -v146
	v_add_f32_e32 v143, v145, v143
	v_lshlrev_b32_e32 v152, 16, v186
	v_and_b32_e32 v151, 0xffff0000, v190
	v_lshlrev_b32_e32 v154, 16, v183
	v_cvt_pk_bf16_f32 v163, v158, v159
	global_load_dwordx4 v[70:73], v[252:253], off offset:64
	ds_write_b128 v222, v[160:163] offset:16384
	s_waitcnt lgkmcnt(1)
	v_lshlrev_b32_e32 v136, 16, v168
	v_cvt_pk_bf16_f32 v216, v140, v141
	v_fmac_f32_e32 v146, v202, v142
	v_fma_f32 v143, v143, 0.5, -v147
	v_add_f32_e32 v148, v150, v148
	v_and_b32_e32 v153, 0xffff0000, v186
	v_lshlrev_b32_e32 v156, 16, v191
	v_and_b32_e32 v155, 0xffff0000, v183
	v_lshlrev_b32_e32 v138, 16, v176
	v_and_b32_e32 v137, 0xffff0000, v168
	v_fmac_f32_e32 v147, v203, v143
	v_fma_f32 v148, v148, 0.5, -v152
	v_add_f32_e32 v149, v151, v149
	v_lshlrev_b32_e32 v158, 16, v187
	v_and_b32_e32 v157, 0xffff0000, v191
	global_load_dwordx4 v[74:77], v[252:253], off offset:2048
	v_lshlrev_b32_e32 v140, 16, v172
	v_and_b32_e32 v139, 0xffff0000, v176
	v_lshlrev_b32_e32 v142, 16, v169
	v_cvt_pk_bf16_f32 v217, v146, v147
	v_fmac_f32_e32 v152, v204, v148
	v_fma_f32 v149, v149, 0.5, -v153
	v_add_f32_e32 v154, v156, v154
	v_and_b32_e32 v159, 0xffff0000, v187
	ds_read_b128 v[180:183], v220 offset:35328
	ds_read_b128 v[184:187], v99 offset:35968
	ds_read_b128 v[188:191], v221 offset:36608
	v_add_f32_e32 v136, v138, v136
	v_and_b32_e32 v141, 0xffff0000, v172
	v_lshlrev_b32_e32 v144, 16, v177
	v_and_b32_e32 v143, 0xffff0000, v169
	v_fmac_f32_e32 v153, v205, v149
	v_fma_f32 v154, v154, 0.5, -v158
	v_add_f32_e32 v155, v157, v155
	global_load_dwordx4 v[78:81], v[252:253], off offset:2112
	v_fma_f32 v136, v136, 0.5, -v140
	v_add_f32_e32 v137, v139, v137
	v_lshlrev_b32_e32 v146, 16, v173
	v_and_b32_e32 v145, 0xffff0000, v177
	v_lshlrev_b32_e32 v148, 16, v170
	v_cvt_pk_bf16_f32 v218, v152, v153
	v_fmac_f32_e32 v158, v206, v154
	v_fma_f32 v155, v155, 0.5, -v159
	v_fmac_f32_e32 v140, v192, v136
	v_fma_f32 v137, v137, 0.5, -v141
	v_add_f32_e32 v142, v144, v142
	v_and_b32_e32 v147, 0xffff0000, v173
	v_lshlrev_b32_e32 v150, 16, v178
	v_and_b32_e32 v149, 0xffff0000, v170
	v_fmac_f32_e32 v159, v207, v155
	global_load_dwordx4 v[82:85], v[224:225], off
	v_mul_f32_e32 v140, 0x4038aa3b, v140
	v_fmac_f32_e32 v141, v193, v137
	v_fma_f32 v142, v142, 0.5, -v146
	v_add_f32_e32 v143, v145, v143
	v_lshlrev_b32_e32 v152, 16, v174
	v_and_b32_e32 v151, 0xffff0000, v178
	v_lshlrev_b32_e32 v154, 16, v171
	v_cvt_pk_bf16_f32 v219, v158, v159
	ds_write_b128 v222, v[216:219] offset:24576
	v_exp_f32_e32 v140, v140
	v_mul_f32_e32 v141, 0x4038aa3b, v141
	v_fmac_f32_e32 v146, v194, v142
	v_fma_f32 v143, v143, 0.5, -v147
	v_add_f32_e32 v148, v150, v148
	v_and_b32_e32 v153, 0xffff0000, v174
	v_lshlrev_b32_e32 v156, 16, v179
	v_and_b32_e32 v155, 0xffff0000, v171
	global_load_dwordx4 v[86:89], v[224:225], off offset:64
	v_add_f32_e32 v140, 1.0, v140
	v_exp_f32_e32 v141, v141
	v_mul_f32_e32 v146, 0x4038aa3b, v146
	v_fmac_f32_e32 v147, v195, v143
	v_fma_f32 v148, v148, 0.5, -v152
	v_add_f32_e32 v149, v151, v149
	v_lshlrev_b32_e32 v158, 16, v175
	v_and_b32_e32 v157, 0xffff0000, v179
	v_rcp_f32_e32 v140, v140
	v_add_f32_e32 v141, 1.0, v141
	v_exp_f32_e32 v146, v146
	v_mul_f32_e32 v147, 0x4038aa3b, v147
	v_fmac_f32_e32 v152, v196, v148
	v_fma_f32 v149, v149, 0.5, -v153
	v_add_f32_e32 v154, v156, v154
	v_and_b32_e32 v159, 0xffff0000, v175
	global_load_dwordx4 v[90:93], v[224:225], off offset:2048
	v_fma_f32 v140, -v140, 2.0, 1.0
	v_rcp_f32_e32 v141, v141
	v_add_f32_e32 v146, 1.0, v146
	v_exp_f32_e32 v147, v147
	v_mul_f32_e32 v152, 0x4038aa3b, v152
	v_fmac_f32_e32 v153, v197, v149
	v_fma_f32 v154, v154, 0.5, -v158
	v_add_f32_e32 v155, v157, v155
	v_fma_f32 v141, -v141, 2.0, 1.0
	v_rcp_f32_e32 v146, v146
	v_add_f32_e32 v147, 1.0, v147
	v_exp_f32_e32 v152, v152
	v_mul_f32_e32 v153, 0x4038aa3b, v153
	v_fmac_f32_e32 v158, v198, v154
	v_fma_f32 v155, v155, 0.5, -v159
	global_load_dwordx4 v[94:97], v[224:225], off offset:2112
	s_waitcnt lgkmcnt(1)
	v_lshlrev_b32_e32 v136, 16, v180
	v_cvt_pk_bf16_f32 v160, v140, v141
	v_fma_f32 v146, -v146, 2.0, 1.0
	v_rcp_f32_e32 v147, v147
	v_add_f32_e32 v152, 1.0, v152
	v_exp_f32_e32 v153, v153
	v_mul_f32_e32 v158, 0x4038aa3b, v158
	v_fmac_f32_e32 v159, v199, v155
	v_lshlrev_b32_e32 v138, 16, v188
	v_and_b32_e32 v137, 0xffff0000, v180
	v_fma_f32 v147, -v147, 2.0, 1.0
	v_rcp_f32_e32 v152, v152
	v_add_f32_e32 v153, 1.0, v153
	v_exp_f32_e32 v158, v158
	v_mul_f32_e32 v159, 0x4038aa3b, v159
	v_lshlrev_b32_e32 v140, 16, v184
	v_and_b32_e32 v139, 0xffff0000, v188
	v_lshlrev_b32_e32 v142, 16, v181
	v_cvt_pk_bf16_f32 v161, v146, v147
	v_fma_f32 v152, -v152, 2.0, 1.0
	v_rcp_f32_e32 v153, v153
	v_add_f32_e32 v158, 1.0, v158
	v_exp_f32_e32 v159, v159
	v_add_f32_e32 v136, v138, v136
	v_and_b32_e32 v141, 0xffff0000, v184
	v_lshlrev_b32_e32 v144, 16, v189
	v_and_b32_e32 v143, 0xffff0000, v181
	v_fma_f32 v153, -v153, 2.0, 1.0
	v_rcp_f32_e32 v158, v158
	v_add_f32_e32 v159, 1.0, v159
	v_fma_f32 v136, v136, 0.5, -v140
	v_add_f32_e32 v137, v139, v137
	v_lshlrev_b32_e32 v146, 16, v185
	v_and_b32_e32 v145, 0xffff0000, v189
	v_lshlrev_b32_e32 v148, 16, v182
	v_cvt_pk_bf16_f32 v162, v152, v153
	v_fma_f32 v158, -v158, 2.0, 1.0
	v_rcp_f32_e32 v159, v159
	v_fmac_f32_e32 v140, v200, v136
	v_fma_f32 v137, v137, 0.5, -v141
	v_add_f32_e32 v142, v144, v142
	v_and_b32_e32 v147, 0xffff0000, v185
	v_lshlrev_b32_e32 v150, 16, v190
	v_and_b32_e32 v149, 0xffff0000, v182
	v_fma_f32 v159, -v159, 2.0, 1.0
	v_fmac_f32_e32 v141, v201, v137
	v_fma_f32 v142, v142, 0.5, -v146
	v_add_f32_e32 v143, v145, v143
	v_lshlrev_b32_e32 v152, 16, v186
	v_and_b32_e32 v151, 0xffff0000, v190
	v_lshlrev_b32_e32 v154, 16, v183
	v_cvt_pk_bf16_f32 v163, v158, v159
	ds_write_b128 v223, v[160:163] offset:16384
	v_cvt_pk_bf16_f32 v216, v140, v141
	v_fmac_f32_e32 v146, v202, v142
	v_fma_f32 v143, v143, 0.5, -v147
	v_add_f32_e32 v148, v150, v148
	v_and_b32_e32 v153, 0xffff0000, v186
	v_lshlrev_b32_e32 v156, 16, v191
	v_and_b32_e32 v155, 0xffff0000, v183
	v_fmac_f32_e32 v147, v203, v143
	v_fma_f32 v148, v148, 0.5, -v152
	v_add_f32_e32 v149, v151, v149
	v_lshlrev_b32_e32 v158, 16, v187
	v_and_b32_e32 v157, 0xffff0000, v191
	v_cvt_pk_bf16_f32 v217, v146, v147
	v_fmac_f32_e32 v152, v204, v148
	v_fma_f32 v149, v149, 0.5, -v153
	v_add_f32_e32 v154, v156, v154
	v_and_b32_e32 v159, 0xffff0000, v187
	v_fmac_f32_e32 v153, v205, v149
	v_fma_f32 v154, v154, 0.5, -v158
	v_add_f32_e32 v155, v157, v155
	v_cvt_pk_bf16_f32 v218, v152, v153
	v_fmac_f32_e32 v158, v206, v154
	v_fma_f32 v155, v155, 0.5, -v159
	v_fmac_f32_e32 v159, v207, v155
	v_cvt_pk_bf16_f32 v219, v158, v159
	ds_write_b128 v223, v[216:219] offset:24576
	v_and_b32_e32 v160, 15, v1
	v_and_b32_e32 v161, -16, v1
	v_or_b32_e32 v162, s0, v160
	v_lshrrev_b32_e32 v163, 2, v1
	v_lshl_add_u32 v161, v162, 7, v161
	ds_read_b128 v[136:139], v161 offset:16384
	ds_read_b128 v[140:143], v161 offset:16448
	ds_read_b128 v[144:147], v161 offset:24576
	ds_read_b128 v[148:151], v161 offset:24640
	v_lshlrev_b32_e32 v162, 2, v160
	v_and_b32_e32 v163, 0x1fffffc, v163
	v_add_u32_e32 v162, 0x22400, v162
	v_add_lshl_u32 v163, v163, s0, 7
	ds_read2_b32 v[152:153], v162 offset0:64 offset1:80
	ds_read2_b32 v[154:155], v162 offset0:96 offset1:112
	ds_read2_b32 v[156:157], v162 offset0:128 offset1:144
	ds_read2_b32 v[158:159], v162 offset0:160 offset1:176
	v_lshl_add_u32 v163, v160, 1, v163
	s_waitcnt vmcnt(14)
	s_waitcnt lgkmcnt(6)
	v_mfma_f32_16x16x32_bf16 v[168:171], v[136:139], v[34:37], 0
	v_mfma_f32_16x16x32_bf16 v[168:171], v[140:143], v[38:41], v[168:171]
	s_waitcnt vmcnt(12)
	v_mfma_f32_16x16x32_bf16 v[172:175], v[136:139], v[42:45], 0
	v_mfma_f32_16x16x32_bf16 v[172:175], v[140:143], v[46:49], v[172:175]
	s_waitcnt lgkmcnt(0)
	s_nop 7
	v_add_f32_e32 v168, v168, v152
	v_mul_f32_e32 v168, 0xbfb8aa3b, v168
	v_add_f32_e32 v169, v169, v152
	v_exp_f32_e32 v168, v168
	v_mul_f32_e32 v169, 0xbfb8aa3b, v169
	v_add_f32_e32 v170, v170, v152
	v_add_f32_e32 v168, 1.0, v168
	v_exp_f32_e32 v169, v169
	v_mul_f32_e32 v170, 0xbfb8aa3b, v170
	v_add_f32_e32 v171, v171, v152
	v_rcp_f32_e32 v168, v168
	v_add_f32_e32 v169, 1.0, v169
	v_exp_f32_e32 v170, v170
	v_mul_f32_e32 v171, 0xbfb8aa3b, v171
	v_fma_mixlo_f16 v168, v168, s47, 0
	v_rcp_f32_e32 v169, v169
	v_add_f32_e32 v170, 1.0, v170
	v_exp_f32_e32 v171, v171
	ds_write_b16 v163, v168 offset:16384
	v_fma_mixlo_f16 v169, v169, s47, 0
	v_rcp_f32_e32 v170, v170
	v_add_f32_e32 v171, 1.0, v171
	ds_write_b16 v163, v169 offset:16512
	v_fma_mixlo_f16 v170, v170, s47, 0
	v_rcp_f32_e32 v171, v171
	ds_write_b16 v163, v170 offset:16640
	v_fma_mixlo_f16 v171, v171, s47, 0
	ds_write_b16 v163, v171 offset:16768
	s_waitcnt vmcnt(10)
	v_mfma_f32_16x16x32_bf16 v[176:179], v[136:139], v[50:53], 0
	v_mfma_f32_16x16x32_bf16 v[176:179], v[140:143], v[54:57], v[176:179]
	v_add_f32_e32 v172, v172, v153
	v_mul_f32_e32 v172, 0xbfb8aa3b, v172
	v_add_f32_e32 v173, v173, v153
	v_exp_f32_e32 v172, v172
	v_mul_f32_e32 v173, 0xbfb8aa3b, v173
	v_add_f32_e32 v174, v174, v153
	v_add_f32_e32 v172, 1.0, v172
	v_exp_f32_e32 v173, v173
	v_mul_f32_e32 v174, 0xbfb8aa3b, v174
	v_add_f32_e32 v175, v175, v153
	v_rcp_f32_e32 v172, v172
	v_add_f32_e32 v173, 1.0, v173
	v_exp_f32_e32 v174, v174
	v_mul_f32_e32 v175, 0xbfb8aa3b, v175
	v_fma_mixlo_f16 v172, v172, s47, 0
	v_rcp_f32_e32 v173, v173
	v_add_f32_e32 v174, 1.0, v174
	v_exp_f32_e32 v175, v175
	ds_write_b16 v163, v172 offset:16416
	v_fma_mixlo_f16 v173, v173, s47, 0
	v_rcp_f32_e32 v174, v174
	v_add_f32_e32 v175, 1.0, v175
	ds_write_b16 v163, v173 offset:16544
	v_fma_mixlo_f16 v174, v174, s47, 0
	v_rcp_f32_e32 v175, v175
	ds_write_b16 v163, v174 offset:16672
	v_fma_mixlo_f16 v175, v175, s47, 0
	ds_write_b16 v163, v175 offset:16800
	s_waitcnt vmcnt(8)
	v_mfma_f32_16x16x32_bf16 v[180:183], v[136:139], v[58:61], 0
	v_mfma_f32_16x16x32_bf16 v[180:183], v[140:143], v[62:65], v[180:183]
	v_add_f32_e32 v176, v176, v154
	v_mul_f32_e32 v176, 0xbfb8aa3b, v176
	v_add_f32_e32 v177, v177, v154
	v_exp_f32_e32 v176, v176
	v_mul_f32_e32 v177, 0xbfb8aa3b, v177
	v_add_f32_e32 v178, v178, v154
	v_add_f32_e32 v176, 1.0, v176
	v_exp_f32_e32 v177, v177
	v_mul_f32_e32 v178, 0xbfb8aa3b, v178
	v_add_f32_e32 v179, v179, v154
	v_rcp_f32_e32 v176, v176
	v_add_f32_e32 v177, 1.0, v177
	v_exp_f32_e32 v178, v178
	v_mul_f32_e32 v179, 0xbfb8aa3b, v179
	v_fma_mixlo_f16 v176, v176, s47, 0
	v_rcp_f32_e32 v177, v177
	v_add_f32_e32 v178, 1.0, v178
	v_exp_f32_e32 v179, v179
	ds_write_b16 v163, v176 offset:16448
	v_fma_mixlo_f16 v177, v177, s47, 0
	v_rcp_f32_e32 v178, v178
	v_add_f32_e32 v179, 1.0, v179
	ds_write_b16 v163, v177 offset:16576
	v_fma_mixlo_f16 v178, v178, s47, 0
	v_rcp_f32_e32 v179, v179
	ds_write_b16 v163, v178 offset:16704
	v_fma_mixlo_f16 v179, v179, s47, 0
	ds_write_b16 v163, v179 offset:16832
	s_waitcnt vmcnt(6)
	v_mfma_f32_16x16x32_bf16 v[184:187], v[144:147], v[66:69], 0
	v_mfma_f32_16x16x32_bf16 v[184:187], v[148:151], v[70:73], v[184:187]
	v_add_f32_e32 v180, v180, v155
	v_mul_f32_e32 v180, 0xbfb8aa3b, v180
	v_add_f32_e32 v181, v181, v155
	v_exp_f32_e32 v180, v180
	v_mul_f32_e32 v181, 0xbfb8aa3b, v181
	v_add_f32_e32 v182, v182, v155
	v_add_f32_e32 v180, 1.0, v180
	v_exp_f32_e32 v181, v181
	v_mul_f32_e32 v182, 0xbfb8aa3b, v182
	v_add_f32_e32 v183, v183, v155
	v_rcp_f32_e32 v180, v180
	v_add_f32_e32 v181, 1.0, v181
	v_exp_f32_e32 v182, v182
	v_mul_f32_e32 v183, 0xbfb8aa3b, v183
	v_fma_mixlo_f16 v180, v180, s47, 0
	v_rcp_f32_e32 v181, v181
	v_add_f32_e32 v182, 1.0, v182
	v_exp_f32_e32 v183, v183
	ds_write_b16 v163, v180 offset:16480
	v_fma_mixlo_f16 v181, v181, s47, 0
	v_rcp_f32_e32 v182, v182
	v_add_f32_e32 v183, 1.0, v183
	ds_write_b16 v163, v181 offset:16608
	v_fma_mixlo_f16 v182, v182, s47, 0
	v_rcp_f32_e32 v183, v183
	ds_write_b16 v163, v182 offset:16736
	v_fma_mixlo_f16 v183, v183, s47, 0
	ds_write_b16 v163, v183 offset:16864
	s_waitcnt vmcnt(4)
	v_mfma_f32_16x16x32_bf16 v[188:191], v[144:147], v[74:77], 0
	v_mfma_f32_16x16x32_bf16 v[188:191], v[148:151], v[78:81], v[188:191]
	v_add_f32_e32 v184, v184, v156
	v_mul_f32_e32 v184, 0xbfb8aa3b, v184
	v_add_f32_e32 v185, v185, v156
	v_exp_f32_e32 v184, v184
	v_mul_f32_e32 v185, 0xbfb8aa3b, v185
	v_add_f32_e32 v186, v186, v156
	v_add_f32_e32 v184, 1.0, v184
	v_exp_f32_e32 v185, v185
	v_mul_f32_e32 v186, 0xbfb8aa3b, v186
	v_add_f32_e32 v187, v187, v156
	v_rcp_f32_e32 v184, v184
	v_add_f32_e32 v185, 1.0, v185
	v_exp_f32_e32 v186, v186
	v_mul_f32_e32 v187, 0xbfb8aa3b, v187
	v_rcp_f32_e32 v185, v185
	v_add_f32_e32 v186, 1.0, v186
	v_exp_f32_e32 v187, v187
	v_cvt_pk_f16_f32 v184, v184, v185
	v_rcp_f32_e32 v186, v186
	v_add_f32_e32 v187, 1.0, v187
	ds_write_b16 v163, v184 offset:24576
	v_rcp_f32_e32 v187, v187
	ds_write_b16_d16_hi v163, v184 offset:24704
	v_cvt_pk_f16_f32 v186, v186, v187
	ds_write_b16 v163, v186 offset:24832
	ds_write_b16_d16_hi v163, v186 offset:24960
	s_waitcnt vmcnt(2)
	v_mfma_f32_16x16x32_bf16 v[192:195], v[144:147], v[82:85], 0
	v_mfma_f32_16x16x32_bf16 v[192:195], v[148:151], v[86:89], v[192:195]
	v_add_f32_e32 v188, v188, v157
	v_mul_f32_e32 v188, 0xbfb8aa3b, v188
	v_add_f32_e32 v189, v189, v157
	v_exp_f32_e32 v188, v188
	v_mul_f32_e32 v189, 0xbfb8aa3b, v189
	v_add_f32_e32 v190, v190, v157
	v_add_f32_e32 v188, 1.0, v188
	v_exp_f32_e32 v189, v189
	v_mul_f32_e32 v190, 0xbfb8aa3b, v190
	v_add_f32_e32 v191, v191, v157
	v_rcp_f32_e32 v188, v188
	v_add_f32_e32 v189, 1.0, v189
	v_exp_f32_e32 v190, v190
	v_mul_f32_e32 v191, 0xbfb8aa3b, v191
	v_rcp_f32_e32 v189, v189
	v_add_f32_e32 v190, 1.0, v190
	v_exp_f32_e32 v191, v191
	v_cvt_pk_f16_f32 v188, v188, v189
	v_rcp_f32_e32 v190, v190
	v_add_f32_e32 v191, 1.0, v191
	ds_write_b16 v163, v188 offset:24608
	v_rcp_f32_e32 v191, v191
	ds_write_b16_d16_hi v163, v188 offset:24736
	v_cvt_pk_f16_f32 v190, v190, v191
	ds_write_b16 v163, v190 offset:24864
	ds_write_b16_d16_hi v163, v190 offset:24992
	s_waitcnt vmcnt(0)
	v_mfma_f32_16x16x32_bf16 v[196:199], v[144:147], v[90:93], 0
	v_mfma_f32_16x16x32_bf16 v[196:199], v[148:151], v[94:97], v[196:199]
	v_add_f32_e32 v192, v192, v158
	v_mul_f32_e32 v192, 0xbfb8aa3b, v192
	v_add_f32_e32 v193, v193, v158
	v_exp_f32_e32 v192, v192
	v_mul_f32_e32 v193, 0xbfb8aa3b, v193
	v_add_f32_e32 v194, v194, v158
	v_add_f32_e32 v192, 1.0, v192
	v_exp_f32_e32 v193, v193
	v_mul_f32_e32 v194, 0xbfb8aa3b, v194
	v_add_f32_e32 v195, v195, v158
	v_rcp_f32_e32 v192, v192
	v_add_f32_e32 v193, 1.0, v193
	v_exp_f32_e32 v194, v194
	v_mul_f32_e32 v195, 0xbfb8aa3b, v195
	v_rcp_f32_e32 v193, v193
	v_add_f32_e32 v194, 1.0, v194
	v_exp_f32_e32 v195, v195
	v_cvt_pk_f16_f32 v192, v192, v193
	v_rcp_f32_e32 v194, v194
	v_add_f32_e32 v195, 1.0, v195
	ds_write_b16 v163, v192 offset:24640
	v_rcp_f32_e32 v195, v195
	ds_write_b16_d16_hi v163, v192 offset:24768
	v_cvt_pk_f16_f32 v194, v194, v195
	ds_write_b16 v163, v194 offset:24896
	ds_write_b16_d16_hi v163, v194 offset:25024
	v_add_f32_e32 v196, v196, v159
	v_mul_f32_e32 v196, 0xbfb8aa3b, v196
	v_add_f32_e32 v197, v197, v159
	v_exp_f32_e32 v196, v196
	v_mul_f32_e32 v197, 0xbfb8aa3b, v197
	v_add_f32_e32 v198, v198, v159
	v_add_f32_e32 v196, 1.0, v196
	v_exp_f32_e32 v197, v197
	v_mul_f32_e32 v198, 0xbfb8aa3b, v198
	v_add_f32_e32 v199, v199, v159
	v_rcp_f32_e32 v196, v196
	v_add_f32_e32 v197, 1.0, v197
	v_exp_f32_e32 v198, v198
	v_mul_f32_e32 v199, 0xbfb8aa3b, v199
	v_rcp_f32_e32 v197, v197
	v_add_f32_e32 v198, 1.0, v198
	v_exp_f32_e32 v199, v199
	v_cvt_pk_f16_f32 v196, v196, v197
	v_rcp_f32_e32 v198, v198
	v_add_f32_e32 v199, 1.0, v199
	ds_write_b16 v163, v196 offset:24672
	v_rcp_f32_e32 v199, v199
	ds_write_b16_d16_hi v163, v196 offset:24800
	v_cvt_pk_f16_f32 v198, v198, v199
	ds_write_b16 v163, v198 offset:24928
	ds_write_b16_d16_hi v163, v198 offset:25056
